# v sweep gathers: scalar-base global_load form, one v_lshl_add_u32 per expert row address (was shift + 64-bit vector add), per-step slice bases computed on the SALU
# baseline (speedup 1.0000x reference)
.LBB0_1137:
	v_or_b32_e32 v8, s4, v2
	v_or_b32_e32 v10, s3, v3
	v_ashrrev_i32_e32 v9, 31, v8
	v_ashrrev_i32_e32 v11, 31, v10
	v_lshlrev_b64 v[8:9], 9, v[8:9]
	v_lshl_add_u32 v19, s4, 8, v18
	v_lshlrev_b64 v[10:11], 9, v[10:11]
	v_lshl_add_u64 v[8:9], v[0:1], 0, v[8:9]
	v_lshl_add_u32 v20, s3, 8, v18
	ds_read_u16 v23, v19
	ds_read_u16 v38, v20
	v_lshl_add_u64 v[10:11], v[0:1], 0, v[10:11]
	global_load_dword v30, v[8:9], off
	global_load_dword v31, v[10:11], off
	s_add_i32 s0, s3, 2
	s_add_i32 s1, s4, 2
	s_add_i32 s11, s3, 4
	s_add_i32 s18, s4, 4
	s_add_i32 s39, s3, 6
	s_add_i32 s41, s4, 6
	v_or_b32_e32 v12, s0, v3
	v_or_b32_e32 v14, s1, v2
	v_or_b32_e32 v16, s11, v3
	v_or_b32_e32 v24, s18, v2
	v_or_b32_e32 v26, s39, v3
	v_or_b32_e32 v28, s41, v2
	v_ashrrev_i32_e32 v15, 31, v14
	v_ashrrev_i32_e32 v13, 31, v12
	v_ashrrev_i32_e32 v25, 31, v24
	v_ashrrev_i32_e32 v17, 31, v16
	v_ashrrev_i32_e32 v29, 31, v28
	v_ashrrev_i32_e32 v27, 31, v26
	v_lshlrev_b64 v[12:13], 9, v[12:13]
	v_lshlrev_b64 v[14:15], 9, v[14:15]
	v_lshlrev_b64 v[16:17], 9, v[16:17]
	v_lshlrev_b64 v[24:25], 9, v[24:25]
	v_lshlrev_b64 v[26:27], 9, v[26:27]
	v_lshlrev_b64 v[28:29], 9, v[28:29]
	v_lshl_add_u64 v[14:15], v[0:1], 0, v[14:15]
	v_lshl_add_u64 v[12:13], v[0:1], 0, v[12:13]
	v_lshl_add_u64 v[24:25], v[0:1], 0, v[24:25]
	v_lshl_add_u64 v[32:33], v[0:1], 0, v[16:17]
	v_lshl_add_u64 v[28:29], v[0:1], 0, v[28:29]
	v_lshl_add_u64 v[26:27], v[0:1], 0, v[26:27]
	global_load_dword v35, v[10:11], off offset:256
	global_load_dword v36, v[14:15], off
	global_load_dword v37, v[12:13], off
	global_load_dword v17, v[12:13], off offset:256
	global_load_dword v16, v[14:15], off offset:256
	global_load_dword v34, v[8:9], off offset:256
	s_nop 0
	global_load_dword v14, v[24:25], off
	global_load_dword v15, v[32:33], off
	global_load_dword v13, v[32:33], off offset:256
	global_load_dword v10, v[28:29], off
	global_load_dword v11, v[26:27], off
	global_load_dword v9, v[26:27], off offset:256
	global_load_dword v8, v[28:29], off offset:256
	global_load_dword v12, v[24:25], off offset:256
	s_waitcnt lgkmcnt(0)
	v_lshlrev_b32_e32 v25, 16, v38
	v_lshlrev_b32_e32 v24, 16, v23
	v_pk_mul_f32 v[24:25], v[24:25], s[22:23] op_sel_hi:[1,0]
	s_waitcnt vmcnt(16)
	v_mov_b64_e32 v[4:5], s[26:27]
	v_pk_mul_f32 v[26:27], v[24:25], 0.5 op_sel_hi:[1,0]
	v_pk_mul_f32 v[24:25], v[24:25], s[24:25] op_sel_hi:[1,0]
	v_mov_b64_e32 v[6:7], s[42:43]
	v_and_b32_e32 v29, 0x7fffffff, v25
	v_and_b32_e32 v28, 0x7fffffff, v24
	v_pk_mul_f32 v[32:33], v[24:25], v[24:25]
	v_pk_fma_f32 v[38:39], v[28:29], s[28:29], v[4:5] op_sel_hi:[1,0,0]
	v_pk_fma_f32 v[40:41], v[32:33], s[44:45], v[6:7] op_sel_hi:[1,0,0]
	v_pk_fma_f32 v[38:39], v[28:29], v[38:39], s[30:31] op_sel_hi:[1,1,0]
	v_pk_fma_f32 v[40:41], v[32:33], v[40:41], s[46:47] op_sel_hi:[1,1,0]
	v_pk_fma_f32 v[38:39], v[28:29], v[38:39], s[34:35] op_sel_hi:[1,1,0]
	v_pk_fma_f32 v[40:41], v[32:33], v[40:41], s[48:49] op_sel_hi:[1,1,0]
	v_pk_fma_f32 v[38:39], v[28:29], v[38:39], s[36:37] op_sel_hi:[1,1,0]
	v_pk_fma_f32 v[40:41], v[32:33], v[40:41], s[50:51] op_sel_hi:[1,1,0]
	v_pk_fma_f32 v[38:39], v[28:29], v[38:39], s[38:39] op_sel_hi:[1,1,0]
	v_pk_fma_f32 v[32:33], v[32:33], v[40:41], s[52:53] op_sel_hi:[1,1,0]
	v_pk_fma_f32 v[38:39], v[28:29], v[38:39], s[40:41] op_sel_hi:[1,1,0]
	v_pk_fma_f32 v[32:33], v[28:29], v[32:33], v[28:29]
	v_pk_fma_f32 v[28:29], v[28:29], v[38:39], v[28:29]
	v_lshl_add_u32 v42, s1, 8, v18
	v_mul_f32_e32 v23, 0xbfb8aa3b, v29
	v_mul_f32_e32 v38, 0xbfb8aa3b, v28
	v_fma_f32 v39, v29, s29, -v23
	v_rndne_f32_e32 v40, v23
	v_fma_f32 v41, v28, s29, -v38
	v_rndne_f32_e32 v46, v38
	v_fmac_f32_e32 v39, 0xb2a5705f, v29
	v_sub_f32_e32 v23, v23, v40
	v_fmac_f32_e32 v41, 0xb2a5705f, v28
	v_sub_f32_e32 v38, v38, v46
	v_add_f32_e32 v23, v23, v39
	v_add_f32_e32 v38, v38, v41
	v_cvt_i32_f32_e32 v40, v40
	v_cvt_i32_f32_e32 v46, v46
	v_exp_f32_e32 v23, v23
	v_exp_f32_e32 v38, v38
	v_lshl_add_u32 v43, s0, 8, v18
	v_cmp_nlt_f32_e32 vcc, s31, v28
	v_ldexp_f32 v23, v23, v40
	v_ldexp_f32 v38, v38, v46
	v_cmp_nlt_f32_e64 s[0:1], s31, v29
	v_cndmask_b32_e32 v38, 0, v38, vcc
	v_cmp_ngt_f32_e32 vcc, s33, v28
	v_cndmask_b32_e64 v23, 0, v23, s[0:1]
	v_cmp_ngt_f32_e64 s[0:1], s33, v29
	v_cndmask_b32_e32 v28, v142, v38, vcc
	v_cmp_lt_f32_e64 vcc, |v25|, 1.0
	v_cndmask_b32_e64 v29, v142, v23, s[0:1]
	v_pk_add_f32 v[28:29], v[28:29], 1.0 op_sel_hi:[1,0] neg_lo:[1,0] neg_hi:[1,0]
	v_cmp_lt_f32_e64 s[0:1], |v24|, 1.0
	v_lshl_add_u32 v45, s11, 8, v18
	v_lshl_add_u32 v44, s18, 8, v18
	v_cndmask_b32_e64 v23, v28, v32, s[0:1]
	v_cndmask_b32_e32 v28, v29, v33, vcc
	v_bfi_b32 v25, s27, v28, v25
	v_bfi_b32 v24, s27, v23, v24
	v_pk_add_f32 v[24:25], v[24:25], 1.0 op_sel_hi:[1,0]
	v_lshl_add_u32 v22, s39, 8, v18
	v_pk_mul_f32 v[24:25], v[26:27], v[24:25]
	v_lshl_add_u32 v21, s41, 8, v18
	s_waitcnt vmcnt(14)
	v_pk_mul_f32 v[24:25], v[30:31], v[24:25]
	s_add_i32 s4, s4, 8
	v_pk_mul_f32 v[24:25], v[24:25], s[54:55] op_sel_hi:[1,0]
	s_add_i32 s3, s3, 8
	v_and_b32_sdwa v26, v24, v143 dst_sel:DWORD dst_unused:UNUSED_PAD src0_sel:WORD_1 src1_sel:DWORD
	v_and_b32_sdwa v23, v25, v143 dst_sel:DWORD dst_unused:UNUSED_PAD src0_sel:WORD_1 src1_sel:DWORD
	v_add3_u32 v24, v24, v26, s35
	v_add3_u32 v23, v25, v23, s35
	ds_write_b16_d16_hi v19, v24
	ds_write_b16_d16_hi v20, v23
	ds_read_u16 v23, v20 offset:128
	ds_read_u16 v24, v19 offset:128
	s_add_i32 s5, s5, -8
	s_cmp_eq_u32 s5, 0
	s_waitcnt lgkmcnt(1)
	v_lshlrev_b32_e32 v25, 16, v23
	s_waitcnt lgkmcnt(0)
	v_lshlrev_b32_e32 v24, 16, v24
	v_pk_mul_f32 v[24:25], v[24:25], s[22:23] op_sel_hi:[1,0]
	s_nop 0
	v_pk_mul_f32 v[26:27], v[24:25], 0.5 op_sel_hi:[1,0]
	v_pk_mul_f32 v[24:25], v[24:25], s[24:25] op_sel_hi:[1,0]
	s_nop 0
	v_and_b32_e32 v29, 0x7fffffff, v25
	v_and_b32_e32 v28, 0x7fffffff, v24
	v_pk_mul_f32 v[30:31], v[24:25], v[24:25]
	v_pk_fma_f32 v[32:33], v[28:29], s[28:29], v[4:5] op_sel_hi:[1,0,0]
	v_pk_fma_f32 v[38:39], v[30:31], s[44:45], v[6:7] op_sel_hi:[1,0,0]
	v_pk_fma_f32 v[32:33], v[28:29], v[32:33], s[30:31] op_sel_hi:[1,1,0]
	v_pk_fma_f32 v[38:39], v[30:31], v[38:39], s[46:47] op_sel_hi:[1,1,0]
	v_pk_fma_f32 v[32:33], v[28:29], v[32:33], s[34:35] op_sel_hi:[1,1,0]
	v_pk_fma_f32 v[38:39], v[30:31], v[38:39], s[48:49] op_sel_hi:[1,1,0]
	v_pk_fma_f32 v[32:33], v[28:29], v[32:33], s[36:37] op_sel_hi:[1,1,0]
	v_pk_fma_f32 v[38:39], v[30:31], v[38:39], s[50:51] op_sel_hi:[1,1,0]
	v_pk_fma_f32 v[32:33], v[28:29], v[32:33], s[38:39] op_sel_hi:[1,1,0]
	v_pk_fma_f32 v[30:31], v[30:31], v[38:39], s[52:53] op_sel_hi:[1,1,0]
	v_pk_fma_f32 v[32:33], v[28:29], v[32:33], s[40:41] op_sel_hi:[1,1,0]
	v_pk_fma_f32 v[30:31], v[28:29], v[30:31], v[28:29]
	v_pk_fma_f32 v[28:29], v[28:29], v[32:33], v[28:29]
	s_nop 0
	v_mul_f32_e32 v23, 0xbfb8aa3b, v29
	v_mul_f32_e32 v32, 0xbfb8aa3b, v28
	v_fma_f32 v33, v29, s29, -v23
	v_rndne_f32_e32 v38, v23
	v_fma_f32 v39, v28, s29, -v32
	v_rndne_f32_e32 v40, v32
	v_fmac_f32_e32 v33, 0xb2a5705f, v29
	v_sub_f32_e32 v23, v23, v38
	v_fmac_f32_e32 v39, 0xb2a5705f, v28
	v_sub_f32_e32 v32, v32, v40
	v_add_f32_e32 v23, v23, v33
	v_add_f32_e32 v32, v32, v39
	v_cvt_i32_f32_e32 v38, v38
	v_cvt_i32_f32_e32 v40, v40
	v_exp_f32_e32 v23, v23
	v_exp_f32_e32 v32, v32
	v_cmp_nlt_f32_e32 vcc, s31, v28
	v_cmp_nlt_f32_e64 s[0:1], s31, v29
	v_ldexp_f32 v23, v23, v38
	v_ldexp_f32 v32, v32, v40
	v_cndmask_b32_e64 v23, 0, v23, s[0:1]
	v_cndmask_b32_e32 v32, 0, v32, vcc
	v_cmp_ngt_f32_e32 vcc, s33, v28
	v_cmp_ngt_f32_e64 s[0:1], s33, v29
	s_nop 0
	v_cndmask_b32_e32 v28, v142, v32, vcc
	v_cndmask_b32_e64 v29, v142, v23, s[0:1]
	v_pk_add_f32 v[28:29], v[28:29], 1.0 op_sel_hi:[1,0] neg_lo:[1,0] neg_hi:[1,0]
	v_cmp_lt_f32_e64 vcc, |v25|, 1.0
	v_cmp_lt_f32_e64 s[0:1], |v24|, 1.0
	s_nop 1
	v_cndmask_b32_e64 v23, v28, v30, s[0:1]
	v_cndmask_b32_e32 v28, v29, v31, vcc
	v_bfi_b32 v25, s27, v28, v25
	v_bfi_b32 v24, s27, v23, v24
	v_pk_add_f32 v[24:25], v[24:25], 1.0 op_sel_hi:[1,0]
	s_nop 0
	v_pk_mul_f32 v[24:25], v[26:27], v[24:25]
	s_waitcnt vmcnt(8)
	v_pk_mul_f32 v[24:25], v[34:35], v[24:25]
	s_nop 0
	v_pk_mul_f32 v[24:25], v[24:25], s[54:55] op_sel_hi:[1,0]
	s_nop 0
	v_and_b32_sdwa v26, v24, v143 dst_sel:DWORD dst_unused:UNUSED_PAD src0_sel:WORD_1 src1_sel:DWORD
	v_and_b32_sdwa v23, v25, v143 dst_sel:DWORD dst_unused:UNUSED_PAD src0_sel:WORD_1 src1_sel:DWORD
	v_add3_u32 v24, v24, v26, s35
	v_add3_u32 v23, v25, v23, s35
	ds_write_b16_d16_hi v19, v24 offset:128
	ds_write_b16_d16_hi v20, v23 offset:128
	ds_read_u16 v19, v43
	ds_read_u16 v20, v42
	s_waitcnt lgkmcnt(1)
	v_lshlrev_b32_e32 v25, 16, v19
	s_waitcnt lgkmcnt(0)
	v_lshlrev_b32_e32 v24, 16, v20
	v_pk_mul_f32 v[24:25], v[24:25], s[22:23] op_sel_hi:[1,0]
	s_nop 0
	v_pk_mul_f32 v[26:27], v[24:25], 0.5 op_sel_hi:[1,0]
	v_pk_mul_f32 v[24:25], v[24:25], s[24:25] op_sel_hi:[1,0]
	s_nop 0
	v_and_b32_e32 v29, 0x7fffffff, v25
	v_and_b32_e32 v28, 0x7fffffff, v24
	v_pk_mul_f32 v[30:31], v[24:25], v[24:25]
	v_pk_fma_f32 v[32:33], v[28:29], s[28:29], v[4:5] op_sel_hi:[1,0,0]
	v_pk_fma_f32 v[34:35], v[30:31], s[44:45], v[6:7] op_sel_hi:[1,0,0]
	v_pk_fma_f32 v[32:33], v[28:29], v[32:33], s[30:31] op_sel_hi:[1,1,0]
	v_pk_fma_f32 v[34:35], v[30:31], v[34:35], s[46:47] op_sel_hi:[1,1,0]
	v_pk_fma_f32 v[32:33], v[28:29], v[32:33], s[34:35] op_sel_hi:[1,1,0]
	v_pk_fma_f32 v[34:35], v[30:31], v[34:35], s[48:49] op_sel_hi:[1,1,0]
	v_pk_fma_f32 v[32:33], v[28:29], v[32:33], s[36:37] op_sel_hi:[1,1,0]
	v_pk_fma_f32 v[34:35], v[30:31], v[34:35], s[50:51] op_sel_hi:[1,1,0]
	v_pk_fma_f32 v[32:33], v[28:29], v[32:33], s[38:39] op_sel_hi:[1,1,0]
	v_pk_fma_f32 v[30:31], v[30:31], v[34:35], s[52:53] op_sel_hi:[1,1,0]
	v_pk_fma_f32 v[32:33], v[28:29], v[32:33], s[40:41] op_sel_hi:[1,1,0]
	v_pk_fma_f32 v[30:31], v[28:29], v[30:31], v[28:29]
	v_pk_fma_f32 v[28:29], v[28:29], v[32:33], v[28:29]
	s_nop 0
	v_mul_f32_e32 v19, 0xbfb8aa3b, v29
	v_mul_f32_e32 v20, 0xbfb8aa3b, v28
	v_fma_f32 v23, v29, s29, -v19
	v_rndne_f32_e32 v32, v19
	v_fma_f32 v33, v28, s29, -v20
	v_rndne_f32_e32 v34, v20
	v_fmac_f32_e32 v23, 0xb2a5705f, v29
	v_sub_f32_e32 v19, v19, v32
	v_fmac_f32_e32 v33, 0xb2a5705f, v28
	v_sub_f32_e32 v20, v20, v34
	v_add_f32_e32 v19, v19, v23
	v_add_f32_e32 v20, v20, v33
	v_cvt_i32_f32_e32 v32, v32
	v_cvt_i32_f32_e32 v34, v34
	v_exp_f32_e32 v19, v19
	v_exp_f32_e32 v20, v20
	v_cmp_nlt_f32_e32 vcc, s31, v28
	v_cmp_nlt_f32_e64 s[0:1], s31, v29
	v_ldexp_f32 v19, v19, v32
	v_ldexp_f32 v20, v20, v34
	v_cndmask_b32_e64 v19, 0, v19, s[0:1]
	v_cndmask_b32_e32 v20, 0, v20, vcc
	v_cmp_ngt_f32_e32 vcc, s33, v28
	v_cmp_ngt_f32_e64 s[0:1], s33, v29
	s_nop 0
	v_cndmask_b32_e32 v28, v142, v20, vcc
	v_cndmask_b32_e64 v29, v142, v19, s[0:1]
	v_pk_add_f32 v[28:29], v[28:29], 1.0 op_sel_hi:[1,0] neg_lo:[1,0] neg_hi:[1,0]
	v_cmp_lt_f32_e64 vcc, |v25|, 1.0
	v_cmp_lt_f32_e64 s[0:1], |v24|, 1.0
	s_nop 0
	v_cndmask_b32_e32 v20, v29, v31, vcc
	v_cndmask_b32_e64 v19, v28, v30, s[0:1]
	v_bfi_b32 v25, s27, v20, v25
	v_bfi_b32 v24, s27, v19, v24
	v_pk_add_f32 v[24:25], v[24:25], 1.0 op_sel_hi:[1,0]
	s_nop 0
	v_pk_mul_f32 v[24:25], v[26:27], v[24:25]
	s_nop 0
	v_pk_mul_f32 v[24:25], v[36:37], v[24:25]
	s_nop 0
	v_pk_mul_f32 v[24:25], v[24:25], s[54:55] op_sel_hi:[1,0]
	s_nop 0
	v_and_b32_sdwa v20, v24, v143 dst_sel:DWORD dst_unused:UNUSED_PAD src0_sel:WORD_1 src1_sel:DWORD
	v_and_b32_sdwa v19, v25, v143 dst_sel:DWORD dst_unused:UNUSED_PAD src0_sel:WORD_1 src1_sel:DWORD
	v_add3_u32 v20, v24, v20, s35
	v_add3_u32 v19, v25, v19, s35
	ds_write_b16_d16_hi v42, v20
	ds_write_b16_d16_hi v43, v19
	ds_read_u16 v19, v43 offset:128
	ds_read_u16 v20, v42 offset:128
	s_waitcnt lgkmcnt(1)
	v_lshlrev_b32_e32 v25, 16, v19
	s_waitcnt lgkmcnt(0)
	v_lshlrev_b32_e32 v24, 16, v20
	v_pk_mul_f32 v[24:25], v[24:25], s[22:23] op_sel_hi:[1,0]
	s_nop 0
	v_pk_mul_f32 v[26:27], v[24:25], 0.5 op_sel_hi:[1,0]
	v_pk_mul_f32 v[24:25], v[24:25], s[24:25] op_sel_hi:[1,0]
	s_nop 0
	v_and_b32_e32 v29, 0x7fffffff, v25
	v_and_b32_e32 v28, 0x7fffffff, v24
	v_pk_mul_f32 v[30:31], v[24:25], v[24:25]
	v_pk_fma_f32 v[32:33], v[28:29], s[28:29], v[4:5] op_sel_hi:[1,0,0]
	v_pk_fma_f32 v[34:35], v[30:31], s[44:45], v[6:7] op_sel_hi:[1,0,0]
	v_pk_fma_f32 v[32:33], v[28:29], v[32:33], s[30:31] op_sel_hi:[1,1,0]
	v_pk_fma_f32 v[34:35], v[30:31], v[34:35], s[46:47] op_sel_hi:[1,1,0]
	v_pk_fma_f32 v[32:33], v[28:29], v[32:33], s[34:35] op_sel_hi:[1,1,0]
	v_pk_fma_f32 v[34:35], v[30:31], v[34:35], s[48:49] op_sel_hi:[1,1,0]
	v_pk_fma_f32 v[32:33], v[28:29], v[32:33], s[36:37] op_sel_hi:[1,1,0]
	v_pk_fma_f32 v[34:35], v[30:31], v[34:35], s[50:51] op_sel_hi:[1,1,0]
	v_pk_fma_f32 v[32:33], v[28:29], v[32:33], s[38:39] op_sel_hi:[1,1,0]
	v_pk_fma_f32 v[30:31], v[30:31], v[34:35], s[52:53] op_sel_hi:[1,1,0]
	v_pk_fma_f32 v[32:33], v[28:29], v[32:33], s[40:41] op_sel_hi:[1,1,0]
	v_pk_fma_f32 v[30:31], v[28:29], v[30:31], v[28:29]
	v_pk_fma_f32 v[28:29], v[28:29], v[32:33], v[28:29]
	s_nop 0
	v_mul_f32_e32 v19, 0xbfb8aa3b, v29
	v_mul_f32_e32 v20, 0xbfb8aa3b, v28
	v_fma_f32 v23, v29, s29, -v19
	v_rndne_f32_e32 v32, v19
	v_fma_f32 v33, v28, s29, -v20
	v_rndne_f32_e32 v34, v20
	v_fmac_f32_e32 v23, 0xb2a5705f, v29
	v_sub_f32_e32 v19, v19, v32
	v_fmac_f32_e32 v33, 0xb2a5705f, v28
	v_sub_f32_e32 v20, v20, v34
	v_add_f32_e32 v19, v19, v23
	v_add_f32_e32 v20, v20, v33
	v_cvt_i32_f32_e32 v32, v32
	v_cvt_i32_f32_e32 v34, v34
	v_exp_f32_e32 v19, v19
	v_exp_f32_e32 v20, v20
	v_cmp_nlt_f32_e32 vcc, s31, v28
	v_cmp_nlt_f32_e64 s[0:1], s31, v29
	v_ldexp_f32 v19, v19, v32
	v_ldexp_f32 v20, v20, v34
	v_cndmask_b32_e64 v19, 0, v19, s[0:1]
	v_cndmask_b32_e32 v20, 0, v20, vcc
	v_cmp_ngt_f32_e32 vcc, s33, v28
	v_cmp_ngt_f32_e64 s[0:1], s33, v29
	s_nop 0
	v_cndmask_b32_e32 v28, v142, v20, vcc
	v_cndmask_b32_e64 v29, v142, v19, s[0:1]
	v_pk_add_f32 v[28:29], v[28:29], 1.0 op_sel_hi:[1,0] neg_lo:[1,0] neg_hi:[1,0]
	v_cmp_lt_f32_e64 vcc, |v25|, 1.0
	v_cmp_lt_f32_e64 s[0:1], |v24|, 1.0
	s_nop 0
	v_cndmask_b32_e32 v20, v29, v31, vcc
	v_cndmask_b32_e64 v19, v28, v30, s[0:1]
	v_bfi_b32 v25, s27, v20, v25
	v_bfi_b32 v24, s27, v19, v24
	v_pk_add_f32 v[24:25], v[24:25], 1.0 op_sel_hi:[1,0]
	s_nop 0
	v_pk_mul_f32 v[24:25], v[26:27], v[24:25]
	s_nop 0
	v_pk_mul_f32 v[16:17], v[16:17], v[24:25]
	s_nop 0
	v_pk_mul_f32 v[16:17], v[16:17], s[54:55] op_sel_hi:[1,0]
	s_nop 0
	v_and_b32_sdwa v20, v16, v143 dst_sel:DWORD dst_unused:UNUSED_PAD src0_sel:WORD_1 src1_sel:DWORD
	v_and_b32_sdwa v19, v17, v143 dst_sel:DWORD dst_unused:UNUSED_PAD src0_sel:WORD_1 src1_sel:DWORD
	v_add3_u32 v16, v16, v20, s35
	v_add3_u32 v17, v17, v19, s35
	ds_write_b16_d16_hi v42, v16 offset:128
	ds_write_b16_d16_hi v43, v17 offset:128
	ds_read_u16 v16, v45
	ds_read_u16 v19, v44
	s_waitcnt lgkmcnt(1)
	v_lshlrev_b32_e32 v17, 16, v16
	s_waitcnt lgkmcnt(0)
	v_lshlrev_b32_e32 v16, 16, v19
	v_pk_mul_f32 v[16:17], v[16:17], s[22:23] op_sel_hi:[1,0]
	s_nop 0
	v_pk_mul_f32 v[24:25], v[16:17], 0.5 op_sel_hi:[1,0]
	v_pk_mul_f32 v[16:17], v[16:17], s[24:25] op_sel_hi:[1,0]
	s_nop 0
	v_and_b32_e32 v27, 0x7fffffff, v17
	v_and_b32_e32 v26, 0x7fffffff, v16
	v_pk_mul_f32 v[28:29], v[16:17], v[16:17]
	v_pk_fma_f32 v[30:31], v[26:27], s[28:29], v[4:5] op_sel_hi:[1,0,0]
	v_pk_fma_f32 v[32:33], v[28:29], s[44:45], v[6:7] op_sel_hi:[1,0,0]
	v_pk_fma_f32 v[30:31], v[26:27], v[30:31], s[30:31] op_sel_hi:[1,1,0]
	v_pk_fma_f32 v[32:33], v[28:29], v[32:33], s[46:47] op_sel_hi:[1,1,0]
	v_pk_fma_f32 v[30:31], v[26:27], v[30:31], s[34:35] op_sel_hi:[1,1,0]
	v_pk_fma_f32 v[32:33], v[28:29], v[32:33], s[48:49] op_sel_hi:[1,1,0]
	v_pk_fma_f32 v[30:31], v[26:27], v[30:31], s[36:37] op_sel_hi:[1,1,0]
	v_pk_fma_f32 v[32:33], v[28:29], v[32:33], s[50:51] op_sel_hi:[1,1,0]
	v_pk_fma_f32 v[30:31], v[26:27], v[30:31], s[38:39] op_sel_hi:[1,1,0]
	v_pk_fma_f32 v[28:29], v[28:29], v[32:33], s[52:53] op_sel_hi:[1,1,0]
	v_pk_fma_f32 v[30:31], v[26:27], v[30:31], s[40:41] op_sel_hi:[1,1,0]
	v_pk_fma_f32 v[28:29], v[26:27], v[28:29], v[26:27]
	v_pk_fma_f32 v[26:27], v[26:27], v[30:31], v[26:27]
	s_nop 0
	v_mul_f32_e32 v19, 0xbfb8aa3b, v27
	v_mul_f32_e32 v20, 0xbfb8aa3b, v26
	v_fma_f32 v23, v27, s29, -v19
	v_rndne_f32_e32 v30, v19
	v_fma_f32 v31, v26, s29, -v20
	v_rndne_f32_e32 v32, v20
	v_fmac_f32_e32 v23, 0xb2a5705f, v27
	v_sub_f32_e32 v19, v19, v30
	v_fmac_f32_e32 v31, 0xb2a5705f, v26
	v_sub_f32_e32 v20, v20, v32
	v_add_f32_e32 v19, v19, v23
	v_add_f32_e32 v20, v20, v31
	v_cvt_i32_f32_e32 v30, v30
	v_cvt_i32_f32_e32 v32, v32
	v_exp_f32_e32 v19, v19
	v_exp_f32_e32 v20, v20
	v_cmp_nlt_f32_e32 vcc, s31, v26
	v_cmp_nlt_f32_e64 s[0:1], s31, v27
	v_ldexp_f32 v19, v19, v30
	v_ldexp_f32 v20, v20, v32
	v_cndmask_b32_e64 v19, 0, v19, s[0:1]
	v_cndmask_b32_e32 v20, 0, v20, vcc
	v_cmp_ngt_f32_e32 vcc, s33, v26
	v_cmp_ngt_f32_e64 s[0:1], s33, v27
	s_nop 0
	v_cndmask_b32_e32 v26, v142, v20, vcc
	v_cndmask_b32_e64 v27, v142, v19, s[0:1]
	v_pk_add_f32 v[26:27], v[26:27], 1.0 op_sel_hi:[1,0] neg_lo:[1,0] neg_hi:[1,0]
	v_cmp_lt_f32_e64 vcc, |v17|, 1.0
	v_cmp_lt_f32_e64 s[0:1], |v16|, 1.0
	s_nop 0
	v_cndmask_b32_e32 v20, v27, v29, vcc
	v_cndmask_b32_e64 v19, v26, v28, s[0:1]
	v_bfi_b32 v17, s27, v20, v17
	v_bfi_b32 v16, s27, v19, v16
	v_pk_add_f32 v[16:17], v[16:17], 1.0 op_sel_hi:[1,0]
	s_nop 0
	v_pk_mul_f32 v[16:17], v[24:25], v[16:17]
	s_waitcnt vmcnt(6)
	v_pk_mul_f32 v[14:15], v[14:15], v[16:17]
	s_nop 0
	v_pk_mul_f32 v[14:15], v[14:15], s[54:55] op_sel_hi:[1,0]
	s_nop 0
	v_and_b32_sdwa v17, v14, v143 dst_sel:DWORD dst_unused:UNUSED_PAD src0_sel:WORD_1 src1_sel:DWORD
	v_and_b32_sdwa v16, v15, v143 dst_sel:DWORD dst_unused:UNUSED_PAD src0_sel:WORD_1 src1_sel:DWORD
	v_add3_u32 v14, v14, v17, s35
	v_add3_u32 v15, v15, v16, s35
	ds_write_b16_d16_hi v44, v14
	ds_write_b16_d16_hi v45, v15
	ds_read_u16 v14, v45 offset:128
	ds_read_u16 v16, v44 offset:128
	s_waitcnt lgkmcnt(1)
	v_lshlrev_b32_e32 v15, 16, v14
	s_waitcnt lgkmcnt(0)
	v_lshlrev_b32_e32 v14, 16, v16
	v_pk_mul_f32 v[14:15], v[14:15], s[22:23] op_sel_hi:[1,0]
	s_nop 0
	v_pk_mul_f32 v[16:17], v[14:15], 0.5 op_sel_hi:[1,0]
	v_pk_mul_f32 v[14:15], v[14:15], s[24:25] op_sel_hi:[1,0]
	s_nop 0
	v_and_b32_e32 v25, 0x7fffffff, v15
	v_and_b32_e32 v24, 0x7fffffff, v14
	v_pk_mul_f32 v[26:27], v[14:15], v[14:15]
	v_pk_fma_f32 v[28:29], v[24:25], s[28:29], v[4:5] op_sel_hi:[1,0,0]
	v_pk_fma_f32 v[30:31], v[26:27], s[44:45], v[6:7] op_sel_hi:[1,0,0]
	v_pk_fma_f32 v[28:29], v[24:25], v[28:29], s[30:31] op_sel_hi:[1,1,0]
	v_pk_fma_f32 v[30:31], v[26:27], v[30:31], s[46:47] op_sel_hi:[1,1,0]
	v_pk_fma_f32 v[28:29], v[24:25], v[28:29], s[34:35] op_sel_hi:[1,1,0]
	v_pk_fma_f32 v[30:31], v[26:27], v[30:31], s[48:49] op_sel_hi:[1,1,0]
	v_pk_fma_f32 v[28:29], v[24:25], v[28:29], s[36:37] op_sel_hi:[1,1,0]
	v_pk_fma_f32 v[30:31], v[26:27], v[30:31], s[50:51] op_sel_hi:[1,1,0]
	v_pk_fma_f32 v[28:29], v[24:25], v[28:29], s[38:39] op_sel_hi:[1,1,0]
	v_pk_fma_f32 v[26:27], v[26:27], v[30:31], s[52:53] op_sel_hi:[1,1,0]
	v_pk_fma_f32 v[28:29], v[24:25], v[28:29], s[40:41] op_sel_hi:[1,1,0]
	v_pk_fma_f32 v[26:27], v[24:25], v[26:27], v[24:25]
	v_pk_fma_f32 v[24:25], v[24:25], v[28:29], v[24:25]
	s_nop 0
	v_mul_f32_e32 v19, 0xbfb8aa3b, v25
	v_mul_f32_e32 v20, 0xbfb8aa3b, v24
	v_fma_f32 v23, v25, s29, -v19
	v_rndne_f32_e32 v28, v19
	v_fma_f32 v29, v24, s29, -v20
	v_rndne_f32_e32 v30, v20
	v_fmac_f32_e32 v23, 0xb2a5705f, v25
	v_sub_f32_e32 v19, v19, v28
	v_fmac_f32_e32 v29, 0xb2a5705f, v24
	v_sub_f32_e32 v20, v20, v30
	v_add_f32_e32 v19, v19, v23
	v_add_f32_e32 v20, v20, v29
	v_cvt_i32_f32_e32 v28, v28
	v_cvt_i32_f32_e32 v30, v30
	v_exp_f32_e32 v19, v19
	v_exp_f32_e32 v20, v20
	v_cmp_nlt_f32_e32 vcc, s31, v24
	v_cmp_nlt_f32_e64 s[0:1], s31, v25
	v_ldexp_f32 v19, v19, v28
	v_ldexp_f32 v20, v20, v30
	v_cndmask_b32_e64 v19, 0, v19, s[0:1]
	v_cndmask_b32_e32 v20, 0, v20, vcc
	v_cmp_ngt_f32_e32 vcc, s33, v24
	v_cmp_ngt_f32_e64 s[0:1], s33, v25
	s_nop 0
	v_cndmask_b32_e32 v24, v142, v20, vcc
	v_cndmask_b32_e64 v25, v142, v19, s[0:1]
	v_pk_add_f32 v[24:25], v[24:25], 1.0 op_sel_hi:[1,0] neg_lo:[1,0] neg_hi:[1,0]
	v_cmp_lt_f32_e64 vcc, |v15|, 1.0
	v_cmp_lt_f32_e64 s[0:1], |v14|, 1.0
	s_nop 0
	v_cndmask_b32_e32 v20, v25, v27, vcc
	v_cndmask_b32_e64 v19, v24, v26, s[0:1]
	v_bfi_b32 v15, s27, v20, v15
	v_bfi_b32 v14, s27, v19, v14
	v_pk_add_f32 v[14:15], v[14:15], 1.0 op_sel_hi:[1,0]
	s_nop 0
	v_pk_mul_f32 v[14:15], v[16:17], v[14:15]
	s_waitcnt vmcnt(0)
	v_pk_mul_f32 v[12:13], v[12:13], v[14:15]
	s_nop 0
	v_pk_mul_f32 v[12:13], v[12:13], s[54:55] op_sel_hi:[1,0]
	s_nop 0
	v_and_b32_sdwa v15, v12, v143 dst_sel:DWORD dst_unused:UNUSED_PAD src0_sel:WORD_1 src1_sel:DWORD
	v_and_b32_sdwa v14, v13, v143 dst_sel:DWORD dst_unused:UNUSED_PAD src0_sel:WORD_1 src1_sel:DWORD
	v_add3_u32 v12, v12, v15, s35
	v_add3_u32 v13, v13, v14, s35
	ds_write_b16_d16_hi v44, v12 offset:128
	ds_write_b16_d16_hi v45, v13 offset:128
	ds_read_u16 v12, v22
	ds_read_u16 v14, v21
	s_waitcnt lgkmcnt(1)
	v_lshlrev_b32_e32 v13, 16, v12
	s_waitcnt lgkmcnt(0)
	v_lshlrev_b32_e32 v12, 16, v14
	v_pk_mul_f32 v[12:13], v[12:13], s[22:23] op_sel_hi:[1,0]
	s_nop 0
	v_pk_mul_f32 v[14:15], v[12:13], 0.5 op_sel_hi:[1,0]
	v_pk_mul_f32 v[12:13], v[12:13], s[24:25] op_sel_hi:[1,0]
	s_nop 0
	v_and_b32_e32 v17, 0x7fffffff, v13
	v_and_b32_e32 v16, 0x7fffffff, v12
	v_pk_mul_f32 v[24:25], v[12:13], v[12:13]
	v_pk_fma_f32 v[26:27], v[16:17], s[28:29], v[4:5] op_sel_hi:[1,0,0]
	v_pk_fma_f32 v[28:29], v[24:25], s[44:45], v[6:7] op_sel_hi:[1,0,0]
	v_pk_fma_f32 v[26:27], v[16:17], v[26:27], s[30:31] op_sel_hi:[1,1,0]
	v_pk_fma_f32 v[28:29], v[24:25], v[28:29], s[46:47] op_sel_hi:[1,1,0]
	v_pk_fma_f32 v[26:27], v[16:17], v[26:27], s[34:35] op_sel_hi:[1,1,0]
	v_pk_fma_f32 v[28:29], v[24:25], v[28:29], s[48:49] op_sel_hi:[1,1,0]
	v_pk_fma_f32 v[26:27], v[16:17], v[26:27], s[36:37] op_sel_hi:[1,1,0]
	v_pk_fma_f32 v[28:29], v[24:25], v[28:29], s[50:51] op_sel_hi:[1,1,0]
	v_pk_fma_f32 v[26:27], v[16:17], v[26:27], s[38:39] op_sel_hi:[1,1,0]
	v_pk_fma_f32 v[24:25], v[24:25], v[28:29], s[52:53] op_sel_hi:[1,1,0]
	v_pk_fma_f32 v[26:27], v[16:17], v[26:27], s[40:41] op_sel_hi:[1,1,0]
	v_pk_fma_f32 v[24:25], v[16:17], v[24:25], v[16:17]
	v_pk_fma_f32 v[16:17], v[16:17], v[26:27], v[16:17]
	s_nop 0
	v_mul_f32_e32 v19, 0xbfb8aa3b, v17
	v_mul_f32_e32 v20, 0xbfb8aa3b, v16
	v_fma_f32 v23, v17, s29, -v19
	v_rndne_f32_e32 v26, v19
	v_fma_f32 v27, v16, s29, -v20
	v_rndne_f32_e32 v28, v20
	v_fmac_f32_e32 v23, 0xb2a5705f, v17
	v_sub_f32_e32 v19, v19, v26
	v_fmac_f32_e32 v27, 0xb2a5705f, v16
	v_sub_f32_e32 v20, v20, v28
	v_add_f32_e32 v19, v19, v23
	v_add_f32_e32 v20, v20, v27
	v_cvt_i32_f32_e32 v26, v26
	v_cvt_i32_f32_e32 v28, v28
	v_exp_f32_e32 v19, v19
	v_exp_f32_e32 v20, v20
	v_cmp_nlt_f32_e32 vcc, s31, v16
	v_cmp_nlt_f32_e64 s[0:1], s31, v17
	v_ldexp_f32 v19, v19, v26
	v_ldexp_f32 v20, v20, v28
	v_cndmask_b32_e64 v19, 0, v19, s[0:1]
	v_cndmask_b32_e32 v20, 0, v20, vcc
	v_cmp_ngt_f32_e32 vcc, s33, v16
	v_cmp_ngt_f32_e64 s[0:1], s33, v17
	s_nop 0
	v_cndmask_b32_e32 v16, v142, v20, vcc
	v_cndmask_b32_e64 v17, v142, v19, s[0:1]
	v_pk_add_f32 v[16:17], v[16:17], 1.0 op_sel_hi:[1,0] neg_lo:[1,0] neg_hi:[1,0]
	v_cmp_lt_f32_e64 vcc, |v13|, 1.0
	v_cmp_lt_f32_e64 s[0:1], |v12|, 1.0
	s_nop 0
	v_cndmask_b32_e32 v17, v17, v25, vcc
	v_cndmask_b32_e64 v16, v16, v24, s[0:1]
	v_bfi_b32 v13, s27, v17, v13
	v_bfi_b32 v12, s27, v16, v12
	v_pk_add_f32 v[12:13], v[12:13], 1.0 op_sel_hi:[1,0]
	s_nop 0
	v_pk_mul_f32 v[12:13], v[14:15], v[12:13]
	s_nop 0
	v_pk_mul_f32 v[10:11], v[10:11], v[12:13]
	s_nop 0
	v_pk_mul_f32 v[10:11], v[10:11], s[54:55] op_sel_hi:[1,0]
	s_nop 0
	v_and_b32_sdwa v13, v10, v143 dst_sel:DWORD dst_unused:UNUSED_PAD src0_sel:WORD_1 src1_sel:DWORD
	v_and_b32_sdwa v12, v11, v143 dst_sel:DWORD dst_unused:UNUSED_PAD src0_sel:WORD_1 src1_sel:DWORD
	v_add3_u32 v10, v10, v13, s35
	v_add3_u32 v11, v11, v12, s35
	ds_write_b16_d16_hi v21, v10
	ds_write_b16_d16_hi v22, v11
	ds_read_u16 v10, v22 offset:128
	ds_read_u16 v12, v21 offset:128
	s_waitcnt lgkmcnt(1)
	v_lshlrev_b32_e32 v11, 16, v10
	s_waitcnt lgkmcnt(0)
	v_lshlrev_b32_e32 v10, 16, v12
	v_pk_mul_f32 v[10:11], v[10:11], s[22:23] op_sel_hi:[1,0]
	s_nop 0
	v_pk_mul_f32 v[12:13], v[10:11], 0.5 op_sel_hi:[1,0]
	v_pk_mul_f32 v[10:11], v[10:11], s[24:25] op_sel_hi:[1,0]
	s_nop 0
	v_and_b32_e32 v15, 0x7fffffff, v11
	v_and_b32_e32 v14, 0x7fffffff, v10
	v_pk_fma_f32 v[4:5], v[14:15], s[28:29], v[4:5] op_sel_hi:[1,0,0]
	v_pk_mul_f32 v[16:17], v[10:11], v[10:11]
	v_pk_fma_f32 v[4:5], v[14:15], v[4:5], s[30:31] op_sel_hi:[1,1,0]
	v_pk_fma_f32 v[6:7], v[16:17], s[44:45], v[6:7] op_sel_hi:[1,0,0]
	v_pk_fma_f32 v[4:5], v[14:15], v[4:5], s[34:35] op_sel_hi:[1,1,0]
	v_pk_fma_f32 v[6:7], v[16:17], v[6:7], s[46:47] op_sel_hi:[1,1,0]
	v_pk_fma_f32 v[4:5], v[14:15], v[4:5], s[36:37] op_sel_hi:[1,1,0]
	v_pk_fma_f32 v[6:7], v[16:17], v[6:7], s[48:49] op_sel_hi:[1,1,0]
	v_pk_fma_f32 v[4:5], v[14:15], v[4:5], s[38:39] op_sel_hi:[1,1,0]
	v_pk_fma_f32 v[6:7], v[16:17], v[6:7], s[50:51] op_sel_hi:[1,1,0]
	v_pk_fma_f32 v[4:5], v[14:15], v[4:5], s[40:41] op_sel_hi:[1,1,0]
	v_pk_fma_f32 v[6:7], v[16:17], v[6:7], s[52:53] op_sel_hi:[1,1,0]
	v_pk_fma_f32 v[4:5], v[14:15], v[4:5], v[14:15]
	v_pk_fma_f32 v[6:7], v[14:15], v[6:7], v[14:15]
	v_mul_f32_e32 v14, 0xbfb8aa3b, v5
	v_mul_f32_e32 v15, 0xbfb8aa3b, v4
	v_fma_f32 v16, v5, s29, -v14
	v_rndne_f32_e32 v17, v14
	v_fma_f32 v19, v4, s29, -v15
	v_rndne_f32_e32 v20, v15
	v_fmac_f32_e32 v16, 0xb2a5705f, v5
	v_sub_f32_e32 v14, v14, v17
	v_fmac_f32_e32 v19, 0xb2a5705f, v4
	v_sub_f32_e32 v15, v15, v20
	v_add_f32_e32 v14, v14, v16
	v_add_f32_e32 v15, v15, v19
	v_cvt_i32_f32_e32 v17, v17
	v_cvt_i32_f32_e32 v20, v20
	v_exp_f32_e32 v14, v14
	v_exp_f32_e32 v15, v15
	v_cmp_nlt_f32_e32 vcc, s31, v4
	v_cmp_nlt_f32_e64 s[0:1], s31, v5
	v_ldexp_f32 v14, v14, v17
	v_ldexp_f32 v15, v15, v20
	v_cndmask_b32_e64 v14, 0, v14, s[0:1]
	v_cndmask_b32_e32 v15, 0, v15, vcc
	v_cmp_ngt_f32_e32 vcc, s33, v4
	v_cmp_ngt_f32_e64 s[0:1], s33, v5
	s_nop 0
	v_cndmask_b32_e32 v4, v142, v15, vcc
	v_cndmask_b32_e64 v5, v142, v14, s[0:1]
	v_pk_add_f32 v[4:5], v[4:5], 1.0 op_sel_hi:[1,0] neg_lo:[1,0] neg_hi:[1,0]
	v_cmp_lt_f32_e64 vcc, |v11|, 1.0
	v_cmp_lt_f32_e64 s[0:1], |v10|, 1.0
	s_nop 0
	v_cndmask_b32_e32 v5, v5, v7, vcc
	v_cndmask_b32_e64 v4, v4, v6, s[0:1]
	v_bfi_b32 v5, s27, v5, v11
	v_bfi_b32 v4, s27, v4, v10
	v_pk_add_f32 v[4:5], v[4:5], 1.0 op_sel_hi:[1,0]
	s_nop 0
	v_pk_mul_f32 v[4:5], v[12:13], v[4:5]
	s_nop 0
	v_pk_mul_f32 v[4:5], v[8:9], v[4:5]
	s_nop 0
	v_pk_mul_f32 v[4:5], v[4:5], s[54:55] op_sel_hi:[1,0]
	s_nop 0
	v_and_b32_sdwa v7, v4, v143 dst_sel:DWORD dst_unused:UNUSED_PAD src0_sel:WORD_1 src1_sel:DWORD
	v_and_b32_sdwa v6, v5, v143 dst_sel:DWORD dst_unused:UNUSED_PAD src0_sel:WORD_1 src1_sel:DWORD
	v_add3_u32 v4, v4, v7, s35
	v_add3_u32 v5, v5, v6, s35
	ds_write_b16_d16_hi v21, v4 offset:128
	ds_write_b16_d16_hi v22, v5 offset:128
	s_cbranch_scc0 .LBB0_1137
	v_lshrrev_b32_e32 v0, 2, v85
	v_and_b32_e32 v35, 14, v0
	v_lshlrev_b32_e32 v0, 4, v84
	v_add_u32_e32 v145, v86, v35
	v_and_b32_e32 v72, 0x70, v0
	ds_read_u16 v2, v145
	ds_read_u16 v3, v145 offset:16
	ds_read_u16 v4, v145 offset:32
	ds_read_u16 v5, v145 offset:48
	ds_read_u16 v6, v145 offset:64
	ds_read_u16 v7, v145 offset:80
	ds_read_u16 v8, v145 offset:96
	ds_read_u16 v9, v145 offset:112
	v_lshl_add_u64 v[0:1], s[6:7], 0, v[72:73]
	v_lshl_add_u64 v[32:33], v[0:1], 0, s[56:57]
	s_add_u32 s72, s6, s56
	s_addc_u32 s73, s7, s57
	v_mov_b32_e32 v251, v72
	s_waitcnt lgkmcnt(7)
	v_lshlrev_b32_e32 v0, 7, v2
	v_mov_b32_e32 v1, v73
	s_waitcnt lgkmcnt(6)
	v_lshlrev_b32_e32 v2, 7, v3
	v_mov_b32_e32 v3, v73
	v_lshl_add_u64 v[0:1], v[32:33], 0, v[0:1]
	v_lshl_add_u64 v[2:3], v[32:33], 0, v[2:3]
	global_load_dwordx4 v[28:31], v[0:1], off
	global_load_dwordx4 v[20:23], v[2:3], off
	s_waitcnt lgkmcnt(5)
	v_lshlrev_b32_e32 v0, 7, v4
	v_mov_b32_e32 v1, v73
	s_waitcnt lgkmcnt(4)
	v_lshlrev_b32_e32 v2, 7, v5
	v_mov_b32_e32 v3, v73
	v_lshl_add_u64 v[0:1], v[32:33], 0, v[0:1]
	v_lshl_add_u64 v[2:3], v[32:33], 0, v[2:3]
	global_load_dwordx4 v[24:27], v[0:1], off
	global_load_dwordx4 v[12:15], v[2:3], off
	s_waitcnt lgkmcnt(3)
	v_lshlrev_b32_e32 v0, 7, v6
	v_mov_b32_e32 v1, v73
	s_waitcnt lgkmcnt(2)
	v_lshlrev_b32_e32 v2, 7, v7
	v_mov_b32_e32 v3, v73
	v_lshl_add_u64 v[0:1], v[32:33], 0, v[0:1]
	v_lshl_add_u64 v[2:3], v[32:33], 0, v[2:3]
	global_load_dwordx4 v[16:19], v[0:1], off
	global_load_dwordx4 v[4:7], v[2:3], off
	s_waitcnt lgkmcnt(1)
	v_lshlrev_b32_e32 v0, 7, v8
	v_mov_b32_e32 v1, v73
	s_waitcnt lgkmcnt(0)
	v_lshlrev_b32_e32 v2, 7, v9
	v_mov_b32_e32 v3, v73
	v_lshl_add_u64 v[0:1], v[32:33], 0, v[0:1]
	v_lshl_add_u64 v[2:3], v[32:33], 0, v[2:3]
	global_load_dwordx4 v[8:11], v[0:1], off
	s_nop 0
	global_load_dwordx4 v[0:3], v[2:3], off
	s_lshl_b64 s[0:1], s[60:61], 12
	ds_read_u16 v153, v145 offset:128
	ds_read_u16 v146, v145 offset:144
	ds_read_u16 v151, v145 offset:160
	ds_read_u16 v152, v145 offset:176
	ds_read_u16 v147, v145 offset:192
	ds_read_u16 v148, v145 offset:208
	ds_read_u16 v149, v145 offset:224
	ds_read_u16 v150, v145 offset:240
	s_add_u32 s3, s6, s0
	s_addc_u32 s4, s7, s1
	s_add_u32 s62, s3, 0x18000000
	s_addc_u32 s63, s4, 0
	s_lshl_b64 s[4:5], s[60:61], 11
	s_add_u32 s3, s6, s4
	s_addc_u32 s4, s7, s5
	v_and_b32_e32 v36, 16, v84
	s_add_u32 s64, s3, 0x28000000
	v_cmp_eq_u32_e32 vcc, 0, v36
	v_cmp_lt_i32_e64 s[6:7], v177, v178
	v_xor_b32_e32 v36, 16, v171
	s_addc_u32 s65, s4, 0
	v_add_u32_e32 v77, v77, v35
	v_cndmask_b32_e64 v35, v171, v177, s[6:7]
	v_cmp_lt_i32_e64 s[6:7], v36, v178
	s_add_u32 s60, s70, s0
	v_and_b32_e32 v34, 32, v84
	v_and_b32_e32 v37, 8, v84
	v_cndmask_b32_e64 v36, v171, v36, s[6:7]
	s_addc_u32 s61, s71, s1
	s_mov_b32 s41, 0
	v_cmp_eq_u32_e64 s[0:1], 0, v37
	v_cmp_eq_u32_e64 s[4:5], 0, v34
	v_and_or_b32 v34, v87, 14, v72
	v_lshlrev_b32_e32 v35, 2, v35
	v_lshlrev_b32_e32 v144, 2, v36
	s_mov_b32 s3, 0x10000
	s_movk_i32 s6, 0x80

.Lvsw_skip_gb:
	v_readlane_b32 s100, v252, s39
	v_readlane_b32 s101, v253, s39
	v_ashrrev_i32_e32 v139, 31, v138
	v_lshl_add_u32 v173, s18, 1, v145
	s_lshl_b32 s18, s11, 7
	v_lshlrev_b64 v[138:139], 10, v[138:139]
	v_lshl_add_u64 v[138:139], v[138:139], 0, s[18:19]
	s_lshl_b32 s18, s11, 21
	s_waitcnt lgkmcnt(7)
	v_lshl_add_u32 v156, v153, 7, v251
	s_waitcnt vmcnt(7)
	v_cvt_pk_f32_fp8_e32 v[36:37], v28
	v_cvt_pk_f32_fp8_sdwa v[38:39], v28 src0_sel:WORD_1
	v_cvt_pk_f32_fp8_e32 v[40:41], v29
	v_cvt_pk_f32_fp8_sdwa v[28:29], v29 src0_sel:WORD_1
	v_cvt_pk_f32_fp8_e32 v[42:43], v30
	v_cvt_pk_f32_fp8_sdwa v[44:45], v30 src0_sel:WORD_1
	v_cvt_pk_f32_fp8_e32 v[48:49], v31
	v_cvt_pk_f32_fp8_sdwa v[50:51], v31 src0_sel:WORD_1
	s_add_u32 s74, s72, s18
	s_addc_u32 s75, s73, 0
	s_waitcnt vmcnt(6)
	v_cvt_pk_f32_fp8_e32 v[30:31], v20
	v_cvt_pk_f32_fp8_sdwa v[46:47], v20 src0_sel:WORD_1
	v_cvt_pk_f32_fp8_e32 v[52:53], v21
	v_cvt_pk_f32_fp8_sdwa v[54:55], v21 src0_sel:WORD_1
	v_cvt_pk_f32_fp8_e32 v[58:59], v22
	v_cvt_pk_f32_fp8_sdwa v[60:61], v22 src0_sel:WORD_1
	v_cvt_pk_f32_fp8_e32 v[68:69], v23
	v_cvt_pk_f32_fp8_sdwa v[70:71], v23 src0_sel:WORD_1
	v_lshl_add_u32 v154, s39, 8, v77
	v_or_b32_e32 v138, v138, v34
	s_waitcnt lgkmcnt(6)
	v_lshl_add_u32 v158, v146, 7, v251
	s_waitcnt vmcnt(5)
	v_cvt_pk_f32_fp8_e32 v[20:21], v24
	v_cvt_pk_f32_fp8_sdwa v[22:23], v24 src0_sel:WORD_1
	v_cvt_pk_f32_fp8_e32 v[56:57], v25
	v_cvt_pk_f32_fp8_sdwa v[24:25], v25 src0_sel:WORD_1
	v_cvt_pk_f32_fp8_e32 v[62:63], v26
	v_cvt_pk_f32_fp8_sdwa v[64:65], v26 src0_sel:WORD_1
	v_cvt_pk_f32_fp8_e32 v[78:79], v27
	v_cvt_pk_f32_fp8_sdwa v[80:81], v27 src0_sel:WORD_1
	ds_read_u16 v175, v173
	ds_read_u16 v179, v173 offset:16
	ds_read_u16 v181, v173 offset:32
	ds_read_u16 v183, v173 offset:48
	ds_read_u16 v185, v173 offset:64
	ds_read_u16 v187, v173 offset:80
	ds_read_u16 v189, v173 offset:96
	ds_read_u16 v191, v173 offset:112
	ds_read_u16 v160, v154
	ds_read_u16 v161, v154 offset:16
	ds_read_u16 v169, v154 offset:32
	ds_read_u16 v174, v154 offset:48
	ds_read_u16 v180, v154 offset:64
	ds_read_u16 v182, v154 offset:80
	ds_read_u16 v184, v154 offset:96
	ds_read_u16 v186, v154 offset:112
	ds_read_u16 v153, v173 offset:128
	ds_read_u16 v188, v154 offset:128
	ds_read_u16 v190, v154 offset:144
	ds_read_u16 v192, v154 offset:160
	ds_read_u16 v193, v154 offset:176
	ds_read_u16 v195, v154 offset:192
	ds_read_u16 v197, v154 offset:208
	ds_read_u16 v199, v154 offset:224
	ds_read_u16 v201, v154 offset:240
	v_lshlrev_b64 v[154:155], 2, v[138:139]
	v_lshl_add_u64 v[138:139], v[138:139], 1, s[64:65]
	s_waitcnt lgkmcnt(14)
	v_lshl_add_u32 v204, v151, 7, v251
	s_waitcnt vmcnt(4)
	v_cvt_pk_f32_fp8_e32 v[26:27], v12
	v_cvt_pk_f32_fp8_sdwa v[66:67], v12 src0_sel:WORD_1
	v_cvt_pk_f32_fp8_e32 v[82:83], v13
	v_cvt_pk_f32_fp8_sdwa v[12:13], v13 src0_sel:WORD_1
	v_cvt_pk_f32_fp8_e32 v[86:87], v14
	v_cvt_pk_f32_fp8_sdwa v[88:89], v14 src0_sel:WORD_1
	v_cvt_pk_f32_fp8_e32 v[92:93], v15
	v_cvt_pk_f32_fp8_sdwa v[94:95], v15 src0_sel:WORD_1
	ds_read_u16 v146, v173 offset:144
	ds_read_u16 v151, v173 offset:160
	v_lshl_add_u64 v[166:167], s[62:63], 0, v[154:155]
	global_load_dword v203, v[138:139], off
	v_lshlrev_b32_e32 v168, 16, v160
	v_lshlrev_b32_e32 v170, 16, v161
	v_lshl_add_u64 v[138:139], s[60:61], 0, v[154:155]
	global_load_dwordx4 v[154:157], v156, s[74:75]
	s_nop 0
	global_load_dwordx4 v[158:161], v158, s[74:75]
	v_lshl_add_u32 v238, v152, 7, v251
	v_lshlrev_b32_e32 v172, 16, v169
	v_pk_fma_f32 v[36:37], v[36:37], v[168:169], 0 op_sel_hi:[1,0,0]
	v_pk_fma_f32 v[38:39], v[38:39], v[168:169], 0 op_sel_hi:[1,0,0]
	v_pk_fma_f32 v[40:41], v[40:41], v[168:169], 0 op_sel_hi:[1,0,0]
	v_pk_fma_f32 v[28:29], v[28:29], v[168:169], 0 op_sel_hi:[1,0,0]
	v_pk_fma_f32 v[42:43], v[42:43], v[168:169], 0 op_sel_hi:[1,0,0]
	v_pk_fma_f32 v[44:45], v[44:45], v[168:169], 0 op_sel_hi:[1,0,0]
	v_pk_fma_f32 v[48:49], v[48:49], v[168:169], 0 op_sel_hi:[1,0,0]
	v_pk_fma_f32 v[50:51], v[50:51], v[168:169], 0 op_sel_hi:[1,0,0]
	v_lshl_add_u32 v239, v147, 7, v251
	s_waitcnt vmcnt(6)
	v_cvt_pk_f32_fp8_e32 v[14:15], v16
	v_cvt_pk_f32_fp8_sdwa v[84:85], v16 src0_sel:WORD_1
	v_cvt_pk_f32_fp8_e32 v[90:91], v17
	v_cvt_pk_f32_fp8_sdwa v[16:17], v17 src0_sel:WORD_1
	v_cvt_pk_f32_fp8_e32 v[96:97], v18
	v_cvt_pk_f32_fp8_sdwa v[98:99], v18 src0_sel:WORD_1
	v_cvt_pk_f32_fp8_e32 v[100:101], v19
	v_cvt_pk_f32_fp8_sdwa v[18:19], v19 src0_sel:WORD_1
	ds_read_u16 v152, v173 offset:176
	ds_read_u16 v147, v173 offset:192
	global_load_dwordx2 v[166:167], v[166:167], off
	v_pk_fma_f32 v[30:31], v[30:31], v[170:171], v[36:37] op_sel_hi:[1,0,1]
	v_pk_fma_f32 v[46:47], v[46:47], v[170:171], v[38:39] op_sel_hi:[1,0,1]
	v_pk_fma_f32 v[52:53], v[52:53], v[170:171], v[40:41] op_sel_hi:[1,0,1]
	v_pk_fma_f32 v[28:29], v[54:55], v[170:171], v[28:29] op_sel_hi:[1,0,1]
	v_pk_fma_f32 v[54:55], v[58:59], v[170:171], v[42:43] op_sel_hi:[1,0,1]
	v_pk_fma_f32 v[44:45], v[60:61], v[170:171], v[44:45] op_sel_hi:[1,0,1]
	v_pk_fma_f32 v[48:49], v[68:69], v[170:171], v[48:49] op_sel_hi:[1,0,1]
	v_pk_fma_f32 v[50:51], v[70:71], v[170:171], v[50:51] op_sel_hi:[1,0,1]
	global_load_dwordx4 v[36:39], v204, s[74:75]
	global_load_dwordx4 v[40:43], v238, s[74:75]
	v_lshl_add_u32 v238, v148, 7, v251
	s_waitcnt lgkmcnt(14)
	v_lshlrev_b32_e32 v174, 16, v174
	v_pk_fma_f32 v[20:21], v[20:21], v[172:173], v[30:31] op_sel_hi:[1,0,1]
	v_pk_fma_f32 v[22:23], v[22:23], v[172:173], v[46:47] op_sel_hi:[1,0,1]
	v_pk_fma_f32 v[30:31], v[56:57], v[172:173], v[52:53] op_sel_hi:[1,0,1]
	v_pk_fma_f32 v[24:25], v[24:25], v[172:173], v[28:29] op_sel_hi:[1,0,1]
	v_pk_fma_f32 v[28:29], v[62:63], v[172:173], v[54:55] op_sel_hi:[1,0,1]
	v_pk_fma_f32 v[44:45], v[64:65], v[172:173], v[44:45] op_sel_hi:[1,0,1]
	v_pk_fma_f32 v[46:47], v[78:79], v[172:173], v[48:49] op_sel_hi:[1,0,1]
	v_pk_fma_f32 v[48:49], v[80:81], v[172:173], v[50:51] op_sel_hi:[1,0,1]
	ds_read_u16 v148, v173 offset:208
	v_lshl_add_u32 v54, v149, 7, v251
	ds_read_u16 v149, v173 offset:224
	v_pk_fma_f32 v[20:21], v[26:27], v[174:175], v[20:21] op_sel_hi:[1,0,1]
	v_pk_fma_f32 v[26:27], v[82:83], v[174:175], v[30:31] op_sel_hi:[1,0,1]
	v_pk_fma_f32 v[12:13], v[12:13], v[174:175], v[24:25] op_sel_hi:[1,0,1]
	v_pk_fma_f32 v[24:25], v[86:87], v[174:175], v[28:29] op_sel_hi:[1,0,1]
	v_pk_fma_f32 v[28:29], v[88:89], v[174:175], v[44:45] op_sel_hi:[1,0,1]
	v_pk_fma_f32 v[30:31], v[92:93], v[174:175], v[46:47] op_sel_hi:[1,0,1]
	v_pk_fma_f32 v[52:53], v[94:95], v[174:175], v[48:49] op_sel_hi:[1,0,1]
	global_load_dwordx4 v[44:47], v239, s[74:75]
	s_nop 0
	global_load_dwordx4 v[48:51], v238, s[74:75]
	v_lshlrev_b32_e32 v180, 16, v180
	v_lshl_add_u32 v238, v150, 7, v251
	ds_read_u16 v150, v173 offset:240
	v_pk_fma_f32 v[12:13], v[16:17], v[180:181], v[12:13] op_sel_hi:[1,0,1]
	v_pk_fma_f32 v[16:17], v[96:97], v[180:181], v[24:25] op_sel_hi:[1,0,1]
	v_pk_fma_f32 v[24:25], v[98:99], v[180:181], v[28:29] op_sel_hi:[1,0,1]
	v_pk_fma_f32 v[18:19], v[18:19], v[180:181], v[52:53] op_sel_hi:[1,0,1]
	global_load_dwordx4 v[52:55], v54, s[74:75]
	s_nop 0
	global_load_dwordx4 v[56:59], v238, s[74:75]
	s_waitcnt vmcnt(12)
	v_cvt_pk_f32_fp8_e32 v[102:103], v4
	v_cvt_pk_f32_fp8_sdwa v[104:105], v4 src0_sel:WORD_1
	v_cvt_pk_f32_fp8_e32 v[106:107], v5
	v_cvt_pk_f32_fp8_sdwa v[4:5], v5 src0_sel:WORD_1
	v_cvt_pk_f32_fp8_e32 v[108:109], v6
	v_cvt_pk_f32_fp8_sdwa v[110:111], v6 src0_sel:WORD_1
	v_cvt_pk_f32_fp8_e32 v[114:115], v7
	v_cvt_pk_f32_fp8_sdwa v[116:117], v7 src0_sel:WORD_1
	s_waitcnt vmcnt(11)
	v_cvt_pk_f32_fp8_e32 v[6:7], v8
	v_cvt_pk_f32_fp8_sdwa v[112:113], v8 src0_sel:WORD_1
	v_cvt_pk_f32_fp8_e32 v[118:119], v9
	v_cvt_pk_f32_fp8_sdwa v[8:9], v9 src0_sel:WORD_1
	v_cvt_pk_f32_fp8_e32 v[120:121], v10
	v_cvt_pk_f32_fp8_sdwa v[122:123], v10 src0_sel:WORD_1
	v_cvt_pk_f32_fp8_e32 v[124:125], v11
	v_cvt_pk_f32_fp8_sdwa v[10:11], v11 src0_sel:WORD_1
	s_waitcnt vmcnt(10)
	v_cvt_pk_f32_fp8_e32 v[126:127], v0
	v_cvt_pk_f32_fp8_sdwa v[128:129], v0 src0_sel:WORD_1
	v_cvt_pk_f32_fp8_e32 v[130:131], v1
	v_cvt_pk_f32_fp8_sdwa v[0:1], v1 src0_sel:WORD_1
	s_and_b32 s18, s3, 0xe00000
	v_pk_fma_f32 v[22:23], v[66:67], v[174:175], v[22:23] op_sel_hi:[1,0,1]
	v_cvt_pk_f32_fp8_e32 v[132:133], v2
	v_cvt_pk_f32_fp8_sdwa v[134:135], v2 src0_sel:WORD_1
	v_cvt_pk_f32_fp8_e32 v[136:137], v3
	v_cvt_pk_f32_fp8_sdwa v[2:3], v3 src0_sel:WORD_1
	s_add_u32 s76, s72, s18
	s_addc_u32 s77, s73, 0
	v_lshlrev_b32_e32 v182, 16, v182
	v_pk_fma_f32 v[14:15], v[14:15], v[180:181], v[20:21] op_sel_hi:[1,0,1]
	v_pk_fma_f32 v[20:21], v[84:85], v[180:181], v[22:23] op_sel_hi:[1,0,1]
	v_pk_fma_f32 v[22:23], v[90:91], v[180:181], v[26:27] op_sel_hi:[1,0,1]
	v_pk_fma_f32 v[26:27], v[100:101], v[180:181], v[30:31] op_sel_hi:[1,0,1]
	v_lshl_add_u32 v238, v175, 7, v251
	v_lshlrev_b32_e32 v184, 16, v184
	v_pk_fma_f32 v[4:5], v[4:5], v[182:183], v[12:13] op_sel_hi:[1,0,1]
	v_pk_fma_f32 v[12:13], v[108:109], v[182:183], v[16:17] op_sel_hi:[1,0,1]
	v_pk_fma_f32 v[16:17], v[110:111], v[182:183], v[24:25] op_sel_hi:[1,0,1]
	v_pk_fma_f32 v[24:25], v[114:115], v[182:183], v[26:27] op_sel_hi:[1,0,1]
	v_pk_fma_f32 v[18:19], v[116:117], v[182:183], v[18:19] op_sel_hi:[1,0,1]
	v_lshl_add_u32 v239, v179, 7, v251
	s_waitcnt lgkmcnt(14)
	v_lshlrev_b32_e32 v186, 16, v186
	v_pk_fma_f32 v[4:5], v[8:9], v[184:185], v[4:5] op_sel_hi:[1,0,1]
	v_pk_fma_f32 v[10:11], v[10:11], v[184:185], v[18:19] op_sel_hi:[1,0,1]
	v_lshl_add_u32 v240, v181, 7, v251
	v_pk_fma_f32 v[14:15], v[102:103], v[182:183], v[14:15] op_sel_hi:[1,0,1]
	v_pk_fma_f32 v[20:21], v[104:105], v[182:183], v[20:21] op_sel_hi:[1,0,1]
	v_pk_fma_f32 v[22:23], v[106:107], v[182:183], v[22:23] op_sel_hi:[1,0,1]
	v_pk_fma_f32 v[66:67], v[0:1], v[186:187], v[4:5] op_sel_hi:[1,0,1]
	v_lshl_add_u32 v241, v183, 7, v251
	v_pk_fma_f32 v[6:7], v[6:7], v[184:185], v[14:15] op_sel_hi:[1,0,1]
	v_pk_fma_f32 v[14:15], v[112:113], v[184:185], v[20:21] op_sel_hi:[1,0,1]
	v_pk_fma_f32 v[20:21], v[118:119], v[184:185], v[22:23] op_sel_hi:[1,0,1]
	v_pk_fma_f32 v[8:9], v[120:121], v[184:185], v[12:13] op_sel_hi:[1,0,1]
	v_pk_fma_f32 v[12:13], v[122:123], v[184:185], v[16:17] op_sel_hi:[1,0,1]
	v_pk_fma_f32 v[80:81], v[2:3], v[186:187], v[10:11] op_sel_hi:[1,0,1]
	v_lshl_add_u32 v242, v185, 7, v251
	v_pk_fma_f32 v[16:17], v[124:125], v[184:185], v[24:25] op_sel_hi:[1,0,1]
	v_pk_fma_f32 v[62:63], v[128:129], v[186:187], v[14:15] op_sel_hi:[1,0,1]
	v_pk_fma_f32 v[64:65], v[130:131], v[186:187], v[20:21] op_sel_hi:[1,0,1]
	v_pk_fma_f32 v[70:71], v[134:135], v[186:187], v[12:13] op_sel_hi:[1,0,1]
	global_load_dwordx4 v[28:31], v238, s[76:77]
	global_load_dwordx4 v[20:23], v239, s[76:77]
	s_nop 0
	global_load_dwordx4 v[24:27], v240, s[76:77]
	global_load_dwordx4 v[12:15], v241, s[76:77]
	v_lshl_add_u32 v2, v187, 7, v251
	v_lshl_add_u32 v238, v189, 7, v251
	v_pk_fma_f32 v[60:61], v[126:127], v[186:187], v[6:7] op_sel_hi:[1,0,1]
	v_pk_fma_f32 v[78:79], v[136:137], v[186:187], v[16:17] op_sel_hi:[1,0,1]
	global_load_dwordx4 v[16:19], v242, s[76:77]
	global_load_dwordx4 v[4:7], v2, s[76:77]
	v_lshl_add_u32 v2, v191, 7, v251
	v_pk_fma_f32 v[68:69], v[132:133], v[186:187], v[8:9] op_sel_hi:[1,0,1]
	global_load_dwordx4 v[8:11], v238, s[76:77]
	s_nop 0
	global_load_dwordx4 v[0:3], v2, s[76:77]
	s_waitcnt vmcnt(16)
	v_cvt_pk_f32_fp8_e32 v[82:83], v154
	v_cvt_pk_f32_fp8_sdwa v[84:85], v154 src0_sel:WORD_1
	v_cvt_pk_f32_fp8_e32 v[86:87], v155
	v_cvt_pk_f32_fp8_sdwa v[88:89], v155 src0_sel:WORD_1
	v_cvt_pk_f32_fp8_e32 v[90:91], v156
	v_cvt_pk_f32_fp8_sdwa v[92:93], v156 src0_sel:WORD_1
	v_cvt_pk_f32_fp8_e32 v[94:95], v157
	v_cvt_pk_f32_fp8_sdwa v[96:97], v157 src0_sel:WORD_1
	s_waitcnt vmcnt(15)
	v_cvt_pk_f32_fp8_e32 v[100:101], v158
	v_cvt_pk_f32_fp8_sdwa v[102:103], v158 src0_sel:WORD_1
	v_cvt_pk_f32_fp8_e32 v[104:105], v159
	v_cvt_pk_f32_fp8_sdwa v[106:107], v159 src0_sel:WORD_1
	v_cvt_pk_f32_fp8_e32 v[108:109], v160
	v_cvt_pk_f32_fp8_sdwa v[110:111], v160 src0_sel:WORD_1
	v_cvt_pk_f32_fp8_e32 v[112:113], v161
	v_cvt_pk_f32_fp8_sdwa v[114:115], v161 src0_sel:WORD_1
	s_waitcnt vmcnt(13)
	v_cvt_pk_f32_fp8_e32 v[116:117], v36
	v_cvt_pk_f32_fp8_sdwa v[118:119], v36 src0_sel:WORD_1
	v_cvt_pk_f32_fp8_e32 v[120:121], v37
	v_cvt_pk_f32_fp8_sdwa v[36:37], v37 src0_sel:WORD_1
	v_cvt_pk_f32_fp8_e32 v[122:123], v38
	v_cvt_pk_f32_fp8_sdwa v[124:125], v38 src0_sel:WORD_1
	v_cvt_pk_f32_fp8_e32 v[126:127], v39
	v_cvt_pk_f32_fp8_sdwa v[38:39], v39 src0_sel:WORD_1
	v_lshlrev_b32_e32 v188, 16, v188
	s_waitcnt vmcnt(12)
	v_cvt_pk_f32_fp8_e32 v[128:129], v40
	v_cvt_pk_f32_fp8_sdwa v[130:131], v40 src0_sel:WORD_1
	v_cvt_pk_f32_fp8_e32 v[132:133], v41
	v_cvt_pk_f32_fp8_sdwa v[40:41], v41 src0_sel:WORD_1
	v_cvt_pk_f32_fp8_e32 v[134:135], v42
	v_cvt_pk_f32_fp8_sdwa v[136:137], v42 src0_sel:WORD_1
	v_cvt_pk_f32_fp8_e32 v[154:155], v43
	v_cvt_pk_f32_fp8_sdwa v[42:43], v43 src0_sel:WORD_1
	s_waitcnt lgkmcnt(13)
	v_lshlrev_b32_e32 v190, 16, v190
	v_pk_fma_f32 v[60:61], v[82:83], v[188:189], v[60:61] op_sel_hi:[1,0,1]
	v_pk_fma_f32 v[62:63], v[84:85], v[188:189], v[62:63] op_sel_hi:[1,0,1]
	v_pk_fma_f32 v[64:65], v[86:87], v[188:189], v[64:65] op_sel_hi:[1,0,1]
	v_pk_fma_f32 v[66:67], v[88:89], v[188:189], v[66:67] op_sel_hi:[1,0,1]
	v_pk_fma_f32 v[68:69], v[90:91], v[188:189], v[68:69] op_sel_hi:[1,0,1]
	v_pk_fma_f32 v[70:71], v[92:93], v[188:189], v[70:71] op_sel_hi:[1,0,1]
	v_pk_fma_f32 v[78:79], v[94:95], v[188:189], v[78:79] op_sel_hi:[1,0,1]
	v_pk_fma_f32 v[80:81], v[96:97], v[188:189], v[80:81] op_sel_hi:[1,0,1]
	s_waitcnt vmcnt(11)
	v_cvt_pk_f32_fp8_e32 v[82:83], v44
	v_cvt_pk_f32_fp8_sdwa v[84:85], v44 src0_sel:WORD_1
	v_cvt_pk_f32_fp8_e32 v[86:87], v45
	v_cvt_pk_f32_fp8_sdwa v[44:45], v45 src0_sel:WORD_1
	v_cvt_pk_f32_fp8_e32 v[88:89], v46
	v_cvt_pk_f32_fp8_sdwa v[90:91], v46 src0_sel:WORD_1
	v_cvt_pk_f32_fp8_e32 v[92:93], v47
	v_cvt_pk_f32_fp8_sdwa v[46:47], v47 src0_sel:WORD_1
	s_waitcnt lgkmcnt(12)
	v_lshlrev_b32_e32 v192, 16, v192
	v_pk_fma_f32 v[60:61], v[100:101], v[190:191], v[60:61] op_sel_hi:[1,0,1]
	v_pk_fma_f32 v[62:63], v[102:103], v[190:191], v[62:63] op_sel_hi:[1,0,1]
	v_pk_fma_f32 v[64:65], v[104:105], v[190:191], v[64:65] op_sel_hi:[1,0,1]
	v_pk_fma_f32 v[66:67], v[106:107], v[190:191], v[66:67] op_sel_hi:[1,0,1]
	v_pk_fma_f32 v[68:69], v[108:109], v[190:191], v[68:69] op_sel_hi:[1,0,1]
	v_pk_fma_f32 v[70:71], v[110:111], v[190:191], v[70:71] op_sel_hi:[1,0,1]
	v_pk_fma_f32 v[78:79], v[112:113], v[190:191], v[78:79] op_sel_hi:[1,0,1]
	v_pk_fma_f32 v[80:81], v[114:115], v[190:191], v[80:81] op_sel_hi:[1,0,1]
	s_waitcnt vmcnt(10)
	v_cvt_pk_f32_fp8_e32 v[94:95], v48
	v_cvt_pk_f32_fp8_sdwa v[96:97], v48 src0_sel:WORD_1
	v_cvt_pk_f32_fp8_e32 v[100:101], v49
	v_cvt_pk_f32_fp8_sdwa v[48:49], v49 src0_sel:WORD_1
	v_cvt_pk_f32_fp8_e32 v[102:103], v50
	v_cvt_pk_f32_fp8_sdwa v[104:105], v50 src0_sel:WORD_1
	v_cvt_pk_f32_fp8_e32 v[106:107], v51
	v_cvt_pk_f32_fp8_sdwa v[50:51], v51 src0_sel:WORD_1
	s_waitcnt lgkmcnt(11)
	v_lshlrev_b32_e32 v194, 16, v193
	v_pk_fma_f32 v[60:61], v[116:117], v[192:193], v[60:61] op_sel_hi:[1,0,1]
	v_pk_fma_f32 v[62:63], v[118:119], v[192:193], v[62:63] op_sel_hi:[1,0,1]
	v_pk_fma_f32 v[64:65], v[120:121], v[192:193], v[64:65] op_sel_hi:[1,0,1]
	v_pk_fma_f32 v[36:37], v[36:37], v[192:193], v[66:67] op_sel_hi:[1,0,1]
	v_pk_fma_f32 v[66:67], v[122:123], v[192:193], v[68:69] op_sel_hi:[1,0,1]
	v_pk_fma_f32 v[68:69], v[124:125], v[192:193], v[70:71] op_sel_hi:[1,0,1]
	v_pk_fma_f32 v[70:71], v[126:127], v[192:193], v[78:79] op_sel_hi:[1,0,1]
	v_pk_fma_f32 v[38:39], v[38:39], v[192:193], v[80:81] op_sel_hi:[1,0,1]
	s_waitcnt vmcnt(9)
	v_cvt_pk_f32_fp8_e32 v[78:79], v52
	v_cvt_pk_f32_fp8_sdwa v[80:81], v52 src0_sel:WORD_1
	v_cvt_pk_f32_fp8_e32 v[108:109], v53
	v_cvt_pk_f32_fp8_sdwa v[52:53], v53 src0_sel:WORD_1
	v_cvt_pk_f32_fp8_e32 v[110:111], v54
	v_cvt_pk_f32_fp8_sdwa v[112:113], v54 src0_sel:WORD_1
	v_cvt_pk_f32_fp8_e32 v[114:115], v55
	v_cvt_pk_f32_fp8_sdwa v[54:55], v55 src0_sel:WORD_1
	s_waitcnt lgkmcnt(10)
	v_lshlrev_b32_e32 v196, 16, v195
	v_pk_fma_f32 v[60:61], v[128:129], v[194:195], v[60:61] op_sel_hi:[1,0,1]
	v_pk_fma_f32 v[62:63], v[130:131], v[194:195], v[62:63] op_sel_hi:[1,0,1]
	v_pk_fma_f32 v[64:65], v[132:133], v[194:195], v[64:65] op_sel_hi:[1,0,1]
	v_pk_fma_f32 v[36:37], v[40:41], v[194:195], v[36:37] op_sel_hi:[1,0,1]
	v_pk_fma_f32 v[40:41], v[134:135], v[194:195], v[66:67] op_sel_hi:[1,0,1]
	v_pk_fma_f32 v[66:67], v[136:137], v[194:195], v[68:69] op_sel_hi:[1,0,1]
	v_pk_fma_f32 v[68:69], v[154:155], v[194:195], v[70:71] op_sel_hi:[1,0,1]
	v_pk_fma_f32 v[38:39], v[42:43], v[194:195], v[38:39] op_sel_hi:[1,0,1]
	s_waitcnt vmcnt(8)
	v_cvt_pk_f32_fp8_e32 v[42:43], v56
	v_cvt_pk_f32_fp8_sdwa v[70:71], v56 src0_sel:WORD_1
	v_cvt_pk_f32_fp8_e32 v[116:117], v57
	v_cvt_pk_f32_fp8_sdwa v[56:57], v57 src0_sel:WORD_1
	v_cvt_pk_f32_fp8_e32 v[118:119], v58
	v_cvt_pk_f32_fp8_sdwa v[120:121], v58 src0_sel:WORD_1
	v_cvt_pk_f32_fp8_e32 v[122:123], v59
	v_cvt_pk_f32_fp8_sdwa v[58:59], v59 src0_sel:WORD_1
	s_waitcnt lgkmcnt(9)
	v_lshlrev_b32_e32 v198, 16, v197
	v_pk_fma_f32 v[60:61], v[82:83], v[196:197], v[60:61] op_sel_hi:[1,0,1]
	v_pk_fma_f32 v[62:63], v[84:85], v[196:197], v[62:63] op_sel_hi:[1,0,1]
	v_pk_fma_f32 v[64:65], v[86:87], v[196:197], v[64:65] op_sel_hi:[1,0,1]
	v_pk_fma_f32 v[36:37], v[44:45], v[196:197], v[36:37] op_sel_hi:[1,0,1]
	v_pk_fma_f32 v[40:41], v[88:89], v[196:197], v[40:41] op_sel_hi:[1,0,1]
	v_pk_fma_f32 v[44:45], v[90:91], v[196:197], v[66:67] op_sel_hi:[1,0,1]
	v_pk_fma_f32 v[66:67], v[92:93], v[196:197], v[68:69] op_sel_hi:[1,0,1]
	v_pk_fma_f32 v[38:39], v[46:47], v[196:197], v[38:39] op_sel_hi:[1,0,1]
	s_waitcnt lgkmcnt(8)
	v_lshlrev_b32_e32 v200, 16, v199
	v_pk_fma_f32 v[46:47], v[94:95], v[198:199], v[60:61] op_sel_hi:[1,0,1]
	v_pk_fma_f32 v[60:61], v[96:97], v[198:199], v[62:63] op_sel_hi:[1,0,1]
	v_pk_fma_f32 v[62:63], v[100:101], v[198:199], v[64:65] op_sel_hi:[1,0,1]
	v_pk_fma_f32 v[36:37], v[48:49], v[198:199], v[36:37] op_sel_hi:[1,0,1]
	v_pk_fma_f32 v[40:41], v[102:103], v[198:199], v[40:41] op_sel_hi:[1,0,1]
	v_pk_fma_f32 v[44:45], v[104:105], v[198:199], v[44:45] op_sel_hi:[1,0,1]
	v_pk_fma_f32 v[48:49], v[106:107], v[198:199], v[66:67] op_sel_hi:[1,0,1]
	v_pk_fma_f32 v[38:39], v[50:51], v[198:199], v[38:39] op_sel_hi:[1,0,1]
	s_waitcnt lgkmcnt(7)
	v_lshlrev_b32_e32 v202, 16, v201
	v_pk_fma_f32 v[46:47], v[78:79], v[200:201], v[46:47] op_sel_hi:[1,0,1]
	v_pk_fma_f32 v[50:51], v[80:81], v[200:201], v[60:61] op_sel_hi:[1,0,1]
	v_pk_fma_f32 v[60:61], v[108:109], v[200:201], v[62:63] op_sel_hi:[1,0,1]
	v_pk_fma_f32 v[36:37], v[52:53], v[200:201], v[36:37] op_sel_hi:[1,0,1]
	v_pk_fma_f32 v[40:41], v[110:111], v[200:201], v[40:41] op_sel_hi:[1,0,1]
	v_pk_fma_f32 v[44:45], v[112:113], v[200:201], v[44:45] op_sel_hi:[1,0,1]
	v_pk_fma_f32 v[48:49], v[114:115], v[200:201], v[48:49] op_sel_hi:[1,0,1]
	v_pk_fma_f32 v[38:39], v[54:55], v[200:201], v[38:39] op_sel_hi:[1,0,1]
	v_pk_fma_f32 v[42:43], v[42:43], v[202:203], v[46:47] op_sel_hi:[1,0,1]
	v_pk_fma_f32 v[46:47], v[70:71], v[202:203], v[50:51] op_sel_hi:[1,0,1]
	v_pk_fma_f32 v[50:51], v[116:117], v[202:203], v[60:61] op_sel_hi:[1,0,1]
	v_pk_fma_f32 v[36:37], v[56:57], v[202:203], v[36:37] op_sel_hi:[1,0,1]
	v_pk_fma_f32 v[40:41], v[118:119], v[202:203], v[40:41] op_sel_hi:[1,0,1]
	v_pk_fma_f32 v[44:45], v[120:121], v[202:203], v[44:45] op_sel_hi:[1,0,1]
	v_pk_fma_f32 v[48:49], v[122:123], v[202:203], v[48:49] op_sel_hi:[1,0,1]
	v_pk_fma_f32 v[38:39], v[58:59], v[202:203], v[38:39] op_sel_hi:[1,0,1]
	s_nop 1
	v_permlane32_swap_b32 v42, v40
	v_permlane32_swap_b32 v43, v41
	v_permlane32_swap_b32 v46, v44
	v_permlane32_swap_b32 v47, v45
	v_permlane32_swap_b32 v50, v48
	v_permlane32_swap_b32 v51, v49
	v_permlane32_swap_b32 v36, v38
	v_permlane32_swap_b32 v37, v39
	s_add_i32 s7, s41, 1
	v_pk_add_f32 v[40:41], v[42:43], v[40:41]
	v_pk_add_f32 v[44:45], v[46:47], v[44:45]
	v_pk_add_f32 v[48:49], v[50:51], v[48:49]
	v_pk_add_f32 v[38:39], v[36:37], v[38:39]
	v_lshlrev_b32_e32 v98, 16, v203
	v_and_b32_e32 v99, 0xffff0000, v203
	s_addk_i32 s6, 0x80
	v_permlane16_swap_b32 v40, v48
	v_permlane16_swap_b32 v41, v49
	v_permlane16_swap_b32 v44, v38
	v_permlane16_swap_b32 v45, v39
	v_pk_add_f32 v[36:37], v[44:45], v[38:39]
	v_pk_add_f32 v[38:39], v[40:41], v[48:49]
	s_add_i32 s3, s3, 0x10000
	v_cndmask_b32_e64 v40, v38, v36, s[0:1]
	v_cndmask_b32_e64 v41, v39, v37, s[0:1]
	v_cndmask_b32_e64 v37, v37, v39, s[0:1]
	v_cndmask_b32_e64 v36, v36, v38, s[0:1]
	v_mov_b32_dpp v38, v40 row_ror:8 row_mask:0xf bank_mask:0xf bound_ctrl:1
	v_mov_b32_dpp v39, v41 row_ror:8 row_mask:0xf bank_mask:0xf bound_ctrl:1
	v_pk_add_f32 v[166:167], v[166:167], s[100:101] op_sel_hi:[1,0] neg_lo:[0,1] neg_hi:[0,1]
	s_nop 0
	v_pk_mul_f32 v[166:167], v[166:167], s[100:101] op_sel:[0,1]
	s_nop 0
	v_pk_fma_f32 v[166:167], v[246:247], v[166:167], v[248:249]
	s_nop 0
	v_pk_fma_f32 v[98:99], v[166:167], s[58:59], v[98:99] op_sel_hi:[1,0,1]
	v_pk_add_f32 v[36:37], v[36:37], v[38:39]
	s_mov_b32 s41, s7
	s_cmpk_eq_i32 s7, 0x100
	v_pk_add_f32 v[36:37], v[98:99], v[36:37]
	global_store_dwordx2 v[138:139], v[36:37], off
	s_cbranch_scc0 .LBB0_1139
	s_waitcnt vmcnt(0)
	s_barrier
	v_lshlrev_b64 v[0:1], 12, v[74:75]
	v_lshl_add_u64 v[0:1], s[60:61], 0, v[0:1]
	v_mov_b32_e32 v77, v73
	v_lshl_add_u64 v[64:65], v[0:1], 0, v[76:77]
	v_lshl_add_u64 v[66:67], s[90:91], 0, v[76:77]
	v_lshl_add_u64 v[68:69], s[68:69], 0, v[76:77]
	s_mov_b64 s[100:101], 0x1000
	v_lshl_add_u64 v[64:65], v[64:65], 0, s[100:101]
	global_load_dwordx4 v[206:209], v[66:67], off
	global_load_dwordx4 v[210:213], v[66:67], off offset:1024
	global_load_dwordx4 v[214:217], v[66:67], off offset:2048
	global_load_dwordx4 v[218:221], v[66:67], off offset:3072
	global_load_dwordx4 v[222:225], v[68:69], off
	global_load_dwordx4 v[226:229], v[68:69], off offset:1024
	global_load_dwordx4 v[230:233], v[68:69], off offset:2048
	global_load_dwordx4 v[234:237], v[68:69], off offset:3072
	global_load_dwordx4 v[0:3], v[64:65], off offset:-4096
	global_load_dwordx4 v[4:7], v[64:65], off offset:-3072
	global_load_dwordx4 v[8:11], v[64:65], off offset:-2048
	global_load_dwordx4 v[12:15], v[64:65], off offset:-1024
	global_load_dwordx4 v[40:43], v[66:67], off
	global_load_dwordx4 v[40:43], v[66:67], off
	global_load_dwordx4 v[40:43], v[66:67], off
	global_load_dwordx4 v[40:43], v[66:67], off
	s_mov_b32 s0, 0
